# dense attention loop hand-rewritten: software-pipelined QK(t+1) under softmax/PV(t), 3-slot LDS ring, Q pre-scaled by 0.125*log2e (re-rounded bf16) so exp2 needs no fma, fixed max m=0
# speedup vs baseline: 1.0163x; 1.0163x over previous
; #define MFMA32(a, b, c) __builtin_amdgcn_mfma_f32_32x32x16_bf16((a), (b), (c), 0, 0, 0)
; #define A_LOAD(t, rk, rv) do { const size_t kb_ = (size_t)(t) * 64; \
;     _Pragma("unroll") for (int s = 0; s < NK; ++s) _Pragma("unroll") for (int i = 0; i < KI; ++i) rk[s][i] = *(const u32x4*)(J.k[s] + (kb_ + ksrow + 32 * i) * J.ldk + ksch * 8); \
;     _Pragma("unroll") for (int i = 0; i < VI; ++i) rv[i] = *(const u32x4*)(J.v + (kb_ + vkey0 + (STN / VCH) * i) * J.ldv + vc8); } while (0)
; template <int DV, int NK, int MODE, bool FIXM, int GRP>
; DI void attn_job(char* lds_wg, const AttnJob& J) {
;     ...
;   bf16x8 qf[4];
;   const bf16_t* qrow = J.q + (size_t)r * UW + 8 * h;
; #pragma unroll
;   for (int ds = 0; ds < 4; ++ds) qf[ds] = *(const bf16x8*)(qrow + 16 * ds);
;     ...
;   A_LOAD(J.tile_lo, rk0, rv0); A_WRITE(0, rk0, rv0); if (ONESET) A_LOAD(J.tile_lo + 1, rk0, rv0); else if (DEEP2) A_LOAD(J.tile_lo + 1, rk1, rv1); __syncthreads();
;   const int i16 = lane & 15;
;   const int vrd = h * NDV * 512 + (i16 >> 2) * 64 + (((lane >> 4) & 1) * 16 + (i16 & 3) * 4) * 2;
;   auto compute = [&](const int stage, const int tile) __attribute__((always_inline)) {
;     bool active = true;
;     if (MODE == AM_SWA) { const int k0 = tile * 64; active = !(k0 > J.qpos0 + 31 + 128 || k0 + 63 < J.qpos0 - 128); }
;     if (active) {
;       const char* Kl = lds + stage * 32768 + kstream * 8192 + r * 128;
;       f32x16 sA, sB;
; #pragma unroll
;       for (int i = 0; i < 16; ++i) { sA[i] = 0.f; sB[i] = 0.f; }
;       if (NDV == 2 || FIXM) {
;         bf16x8 ka[4], kb[4];
; #pragma unroll
;         for (int ds = 0; ds < 4; ++ds) { const int co = ((2 * ds + h) ^ ((r >> 1) & 7)) << 4; ka[ds] = *(const bf16x8*)(Kl + co); kb[ds] = *(const bf16x8*)(Kl + 4096 + co); }
; #pragma unroll
;         for (int ds = 0; ds < 4; ++ds) { sA = MFMA32(ka[ds], qf[ds], sA); sB = MFMA32(kb[ds], qf[ds], sB); }
.Lds0_entry:
	s_waitcnt vmcnt(2)
	v_lshlrev_b32_e32 v34, 16, v66
	v_and_b32_e32 v35, 0xffff0000, v66
	v_mul_f32_e32 v34, s7, v34
	v_mul_f32_e32 v35, s7, v35
	v_cvt_pk_bf16_f32 v66, v34, v35
	v_lshlrev_b32_e32 v34, 16, v67
	v_and_b32_e32 v35, 0xffff0000, v67
	v_mul_f32_e32 v34, s7, v34
	v_mul_f32_e32 v35, s7, v35
	v_cvt_pk_bf16_f32 v67, v34, v35
	v_lshlrev_b32_e32 v34, 16, v68
	v_and_b32_e32 v35, 0xffff0000, v68
	v_mul_f32_e32 v34, s7, v34
	v_mul_f32_e32 v35, s7, v35
	v_cvt_pk_bf16_f32 v68, v34, v35
	v_lshlrev_b32_e32 v34, 16, v69
	v_and_b32_e32 v35, 0xffff0000, v69
	v_mul_f32_e32 v34, s7, v34
	v_mul_f32_e32 v35, s7, v35
	v_cvt_pk_bf16_f32 v69, v34, v35
	v_lshlrev_b32_e32 v34, 16, v70
	v_and_b32_e32 v35, 0xffff0000, v70
	v_mul_f32_e32 v34, s7, v34
	v_mul_f32_e32 v35, s7, v35
	v_cvt_pk_bf16_f32 v70, v34, v35
	v_lshlrev_b32_e32 v34, 16, v71
	v_and_b32_e32 v35, 0xffff0000, v71
	v_mul_f32_e32 v34, s7, v34
	v_mul_f32_e32 v35, s7, v35
	v_cvt_pk_bf16_f32 v71, v34, v35
	v_lshlrev_b32_e32 v34, 16, v72
	v_and_b32_e32 v35, 0xffff0000, v72
	v_mul_f32_e32 v34, s7, v34
	v_mul_f32_e32 v35, s7, v35
	v_cvt_pk_bf16_f32 v72, v34, v35
	v_lshlrev_b32_e32 v34, 16, v73
	v_and_b32_e32 v35, 0xffff0000, v73
	v_mul_f32_e32 v34, s7, v34
	v_mul_f32_e32 v35, s7, v35
	v_cvt_pk_bf16_f32 v73, v34, v35
	v_lshlrev_b32_e32 v34, 16, v74
	v_and_b32_e32 v35, 0xffff0000, v74
	v_mul_f32_e32 v34, s7, v34
	v_mul_f32_e32 v35, s7, v35
	v_cvt_pk_bf16_f32 v74, v34, v35
	v_lshlrev_b32_e32 v34, 16, v75
	v_and_b32_e32 v35, 0xffff0000, v75
	v_mul_f32_e32 v34, s7, v34
	v_mul_f32_e32 v35, s7, v35
	v_cvt_pk_bf16_f32 v75, v34, v35
	v_lshlrev_b32_e32 v34, 16, v76
	v_and_b32_e32 v35, 0xffff0000, v76
	v_mul_f32_e32 v34, s7, v34
	v_mul_f32_e32 v35, s7, v35
	v_cvt_pk_bf16_f32 v76, v34, v35
	v_lshlrev_b32_e32 v34, 16, v77
	v_and_b32_e32 v35, 0xffff0000, v77
	v_mul_f32_e32 v34, s7, v34
	v_mul_f32_e32 v35, s7, v35
	v_cvt_pk_bf16_f32 v77, v34, v35
	v_lshlrev_b32_e32 v34, 16, v78
	v_and_b32_e32 v35, 0xffff0000, v78
	v_mul_f32_e32 v34, s7, v34
	v_mul_f32_e32 v35, s7, v35
	v_cvt_pk_bf16_f32 v78, v34, v35
	v_lshlrev_b32_e32 v34, 16, v79
	v_and_b32_e32 v35, 0xffff0000, v79
	v_mul_f32_e32 v34, s7, v34
	v_mul_f32_e32 v35, s7, v35
	v_cvt_pk_bf16_f32 v79, v34, v35
	v_lshlrev_b32_e32 v34, 16, v80
	v_and_b32_e32 v35, 0xffff0000, v80
	v_mul_f32_e32 v34, s7, v34
	v_mul_f32_e32 v35, s7, v35
	v_cvt_pk_bf16_f32 v80, v34, v35
	v_lshlrev_b32_e32 v34, 16, v81
	v_and_b32_e32 v35, 0xffff0000, v81
	v_mul_f32_e32 v34, s7, v34
	v_mul_f32_e32 v35, s7, v35
	v_cvt_pk_bf16_f32 v81, v34, v35
	v_add_u32_e32 v165, v101, v99
	s_mov_b32 s70, 0x78000
	s_mov_b32 s71, 0
	v_lshl_add_u64 v[92:93], v[92:93], 0, s[14:15]
	v_lshl_add_u64 v[90:91], v[90:91], 0, s[14:15]
	v_lshl_add_u64 v[92:93], v[92:93], 0, s[94:95]
	v_lshl_add_u64 v[90:91], v[90:91], 0, s[94:95]
	ds_read_b128 v[106:109], v0
	ds_read_b128 v[110:113], v102
	ds_read_b128 v[120:123], v103
	ds_read_b128 v[124:127], v104
	s_waitcnt vmcnt(0)
	ds_write_b128 v100, v[82:85] offset:16384
	ds_write_b128 v165, v[86:89] offset:24576
	global_load_dwordx4 v[82:85], v[92:93], off offset:1024
	global_load_dwordx4 v[86:89], v[90:91], off offset:1280
	v_lshl_add_u64 v[92:93], v[92:93], 0, s[70:71]
	v_lshl_add_u64 v[90:91], v[90:91], 0, s[70:71]
	s_waitcnt lgkmcnt(5)
	v_mfma_f32_32x32x16_bf16 v[50:65], v[106:109], v[66:69], 0
	s_waitcnt lgkmcnt(4)
	v_mfma_f32_32x32x16_bf16 v[50:65], v[110:113], v[70:73], v[50:65]
	s_waitcnt lgkmcnt(3)
	v_mfma_f32_32x32x16_bf16 v[50:65], v[120:123], v[74:77], v[50:65]
	s_waitcnt lgkmcnt(2)
	v_mfma_f32_32x32x16_bf16 v[50:65], v[124:127], v[78:81], v[50:65]
	ds_read_b128 v[106:109], v0 offset:4096
	ds_read_b128 v[110:113], v102 offset:4096
	ds_read_b128 v[120:123], v103 offset:4096
	ds_read_b128 v[124:127], v104 offset:4096
	s_waitcnt lgkmcnt(3)
	v_mfma_f32_32x32x16_bf16 v[34:49], v[106:109], v[66:69], 0
	s_waitcnt lgkmcnt(2)
	v_mfma_f32_32x32x16_bf16 v[34:49], v[110:113], v[70:73], v[34:49]
	s_waitcnt lgkmcnt(1)
	v_mfma_f32_32x32x16_bf16 v[34:49], v[120:123], v[74:77], v[34:49]
	s_waitcnt lgkmcnt(0)
	v_mfma_f32_32x32x16_bf16 v[34:49], v[124:127], v[78:81], v[34:49]
	v_mov_b32_e32 v164, 0
	s_mov_b32 s38, 0
	s_waitcnt lgkmcnt(0)
	s_barrier
.Lds0_loop:
	ds_read_b128 v[106:109], v0 offset:16384
	ds_read_b128 v[110:113], v102 offset:16384
	ds_read_b128 v[120:123], v103 offset:16384
	ds_read_b128 v[124:127], v104 offset:16384
	ds_read_b64_tr_b16 v[168:169], v98 offset:8192
	ds_read_b64_tr_b16 v[170:171], v98 offset:8448
	ds_read_b64_tr_b16 v[172:173], v98 offset:8704
	ds_read_b64_tr_b16 v[174:175], v98 offset:8960
	ds_read_b64_tr_b16 v[176:177], v98 offset:10240
	ds_read_b64_tr_b16 v[178:179], v98 offset:10496
	ds_read_b64_tr_b16 v[180:181], v98 offset:10752
	ds_read_b64_tr_b16 v[182:183], v98 offset:11008
	s_waitcnt vmcnt(0)
	ds_write_b128 v100, v[82:85] offset:32768
	ds_write_b128 v165, v[86:89] offset:40960
	s_add_i32 s39, s38, 3
	s_cmp_lt_u32 s39, s96
	s_cbranch_scc0 .Lds0_sk0
	global_load_dwordx4 v[82:85], v[92:93], off offset:1024
	global_load_dwordx4 v[86:89], v[90:91], off offset:1280
	v_lshl_add_u64 v[92:93], v[92:93], 0, s[70:71]
	v_lshl_add_u64 v[90:91], v[90:91], 0, s[70:71]
; template <int DV, int NK, int MODE, bool FIXM, int GRP>
; DI void attn_job(char* lds_wg, const AttnJob& J) {
;     ...
;       if (NDV == 2 || FIXM) {
;         bf16x8 ka[4], kb[4];
; #pragma unroll
;         for (int ds = 0; ds < 4; ++ds) { const int co = ((2 * ds + h) ^ ((r >> 1) & 7)) << 4; ka[ds] = *(const bf16x8*)(Kl + co); kb[ds] = *(const bf16x8*)(Kl + 4096 + co); }
; #pragma unroll
;         for (int ds = 0; ds < 4; ++ds) { sA = MFMA32(ka[ds], qf[ds], sA); sB = MFMA32(kb[ds], qf[ds], sB); }
;         __builtin_amdgcn_sched_group_barrier(0x100, 4, 0); __builtin_amdgcn_sched_group_barrier(0x008, 2, 0);
;         __builtin_amdgcn_sched_group_barrier(0x100, 2, 0); __builtin_amdgcn_sched_group_barrier(0x008, 2, 0);
;         __builtin_amdgcn_sched_group_barrier(0x100, 2, 0); __builtin_amdgcn_sched_group_barrier(0x008, 4, 0);
;       } else {
; #pragma unroll
;         for (int ds = 0; ds < 4; ++ds) {
;           const int co = ((2 * ds + h) ^ ((r >> 1) & 7)) << 4;
;           const bf16x8 ka = *(const bf16x8*)(Kl + co), kb = *(const bf16x8*)(Kl + 4096 + co);
;           sA = MFMA32(ka, qf[ds], sA); sB = MFMA32(kb, qf[ds], sB);
;         }
;       }
;       if (MODE == AM_SWA) {
;         const int qa = J.qpos0 + r, kbase = tile * 64 + 8 * h;
; #pragma unroll
;         for (int i = 0; i < 16; ++i) {
;           const int ka_ = kbase + 16 * (i >> 3) + (i & 7);
;           int d0 = qa - ka_; d0 = d0 < 0 ? -d0 : d0; if (d0 > 128) sA[i] = -INFINITY;
;           int d1 = qa - (ka_ + 32); d1 = d1 < 0 ? -d1 : d1; if (d1 > 128) sB[i] = -INFINITY;
;         }
;       }
;       if (FIXM) {
;         const float nm = -J.m_init;
; #pragma unroll
;         for (int i = 0; i < 16; ++i) { sA[i] = __builtin_amdgcn_exp2f(fmaf(sA[i], C, nm)); sB[i] = __builtin_amdgcn_exp2f(fmaf(sB[i], C, nm)); l += sA[i] + sB[i]; }
;     ...
;       bf16x8 pf[4];
;       { u32x4 w;
;         w.x = cvtpk(sA[0], sA[1]); w.y = cvtpk(sA[2], sA[3]); w.z = cvtpk(sA[4], sA[5]); w.w = cvtpk(sA[6], sA[7]); pf[0] = __builtin_bit_cast(bf16x8, w);
;         w.x = cvtpk(sA[8], sA[9]); w.y = cvtpk(sA[10], sA[11]); w.z = cvtpk(sA[12], sA[13]); w.w = cvtpk(sA[14], sA[15]); pf[1] = __builtin_bit_cast(bf16x8, w);
;         w.x = cvtpk(sB[0], sB[1]); w.y = cvtpk(sB[2], sB[3]); w.z = cvtpk(sB[4], sB[5]); w.w = cvtpk(sB[6], sB[7]); pf[2] = __builtin_bit_cast(bf16x8, w);
.Lds0_sk0:
	v_exp_f32_e32 v50, v50
	v_exp_f32_e32 v51, v51
	v_exp_f32_e32 v52, v52
	v_exp_f32_e32 v53, v53
	v_exp_f32_e32 v54, v54
	v_exp_f32_e32 v55, v55
	v_exp_f32_e32 v56, v56
	v_exp_f32_e32 v57, v57
	s_waitcnt lgkmcnt(13)
	v_mfma_f32_32x32x16_bf16 v[136:151], v[106:109], v[66:69], 0
	v_cvt_pk_bf16_f32 v152, v50, v51
	v_cvt_pk_bf16_f32 v153, v52, v53
	v_cvt_pk_bf16_f32 v154, v54, v55
	v_cvt_pk_bf16_f32 v155, v56, v57
	v_add_f32_e32 v115, v50, v115
	v_add_f32_e32 v115, v51, v115
	s_waitcnt lgkmcnt(12)
	v_mfma_f32_32x32x16_bf16 v[136:151], v[110:113], v[70:73], v[136:151]
	v_exp_f32_e32 v58, v58
	v_exp_f32_e32 v59, v59
	v_exp_f32_e32 v60, v60
	v_exp_f32_e32 v61, v61
	v_add_f32_e32 v164, v52, v164
	v_add_f32_e32 v164, v53, v164
	s_waitcnt lgkmcnt(11)
	v_mfma_f32_32x32x16_bf16 v[136:151], v[120:123], v[74:77], v[136:151]
	v_exp_f32_e32 v62, v62
	v_exp_f32_e32 v63, v63
	v_exp_f32_e32 v64, v64
	v_exp_f32_e32 v65, v65
	v_add_f32_e32 v115, v54, v115
	v_add_f32_e32 v115, v55, v115
	s_waitcnt lgkmcnt(10)
	v_mfma_f32_32x32x16_bf16 v[136:151], v[124:127], v[78:81], v[136:151]
	ds_read_b128 v[106:109], v0 offset:20480
	ds_read_b128 v[110:113], v102 offset:20480
	ds_read_b128 v[120:123], v103 offset:20480
	ds_read_b128 v[124:127], v104 offset:20480
	v_add_f32_e32 v164, v56, v164
	v_add_f32_e32 v164, v57, v164
	s_waitcnt lgkmcnt(12)
	v_mfma_f32_32x32x16_bf16 v[18:33], v[168:171], v[152:155], v[18:33]
	v_cvt_pk_bf16_f32 v156, v58, v59
	v_cvt_pk_bf16_f32 v157, v60, v61
	v_cvt_pk_bf16_f32 v158, v62, v63
	v_cvt_pk_bf16_f32 v159, v64, v65
	v_add_f32_e32 v115, v58, v115
	v_add_f32_e32 v115, v59, v115
	s_waitcnt lgkmcnt(10)
	v_mfma_f32_32x32x16_bf16 v[2:17], v[172:175], v[152:155], v[2:17]
	v_add_f32_e32 v164, v60, v164
	v_add_f32_e32 v164, v61, v164
	v_add_f32_e32 v164, v62, v164
	v_add_f32_e32 v164, v63, v164
	v_add_f32_e32 v164, v64, v164
	v_add_f32_e32 v164, v65, v164
	s_waitcnt lgkmcnt(8)
	v_mfma_f32_32x32x16_bf16 v[18:33], v[176:179], v[156:159], v[18:33]
	v_exp_f32_e32 v34, v34
	v_exp_f32_e32 v35, v35
	v_exp_f32_e32 v36, v36
	v_exp_f32_e32 v37, v37
	s_waitcnt lgkmcnt(6)
	v_mfma_f32_32x32x16_bf16 v[2:17], v[180:183], v[156:159], v[2:17]
	ds_read_b64_tr_b16 v[168:169], v98 offset:12288
	ds_read_b64_tr_b16 v[170:171], v98 offset:12544
	ds_read_b64_tr_b16 v[172:173], v98 offset:12800
	ds_read_b64_tr_b16 v[174:175], v98 offset:13056
	ds_read_b64_tr_b16 v[176:177], v98 offset:14336
	ds_read_b64_tr_b16 v[178:179], v98 offset:14592
	ds_read_b64_tr_b16 v[180:181], v98 offset:14848
	ds_read_b64_tr_b16 v[182:183], v98 offset:15104
	v_exp_f32_e32 v38, v38
	v_exp_f32_e32 v39, v39
	v_exp_f32_e32 v40, v40
	v_exp_f32_e32 v41, v41
	s_waitcnt lgkmcnt(11)
	v_mfma_f32_32x32x16_bf16 v[50:65], v[106:109], v[66:69], 0
	v_cvt_pk_bf16_f32 v160, v34, v35
	v_cvt_pk_bf16_f32 v161, v36, v37
	v_cvt_pk_bf16_f32 v162, v38, v39
	v_cvt_pk_bf16_f32 v163, v40, v41
	v_add_f32_e32 v115, v34, v115
	v_add_f32_e32 v115, v35, v115
	s_waitcnt lgkmcnt(10)
	v_mfma_f32_32x32x16_bf16 v[50:65], v[110:113], v[70:73], v[50:65]
	v_exp_f32_e32 v42, v42
	v_exp_f32_e32 v43, v43
	v_exp_f32_e32 v44, v44
	v_exp_f32_e32 v45, v45
	v_add_f32_e32 v164, v36, v164
	v_add_f32_e32 v164, v37, v164
	s_waitcnt lgkmcnt(9)
	v_mfma_f32_32x32x16_bf16 v[50:65], v[120:123], v[74:77], v[50:65]
	v_exp_f32_e32 v46, v46
	v_exp_f32_e32 v47, v47
	v_exp_f32_e32 v48, v48
	v_exp_f32_e32 v49, v49
	v_add_f32_e32 v115, v38, v115
	v_add_f32_e32 v115, v39, v115
	s_waitcnt lgkmcnt(8)
	v_mfma_f32_32x32x16_bf16 v[50:65], v[124:127], v[78:81], v[50:65]
	v_cvt_pk_bf16_f32 v184, v42, v43
	v_cvt_pk_bf16_f32 v185, v44, v45
	v_cvt_pk_bf16_f32 v186, v46, v47
	v_cvt_pk_bf16_f32 v187, v48, v49
	v_add_f32_e32 v164, v40, v164
	v_add_f32_e32 v164, v41, v164
	s_waitcnt lgkmcnt(6)
	v_mfma_f32_32x32x16_bf16 v[18:33], v[168:171], v[160:163], v[18:33]
	v_add_f32_e32 v115, v42, v115
	v_add_f32_e32 v115, v43, v115
	v_add_f32_e32 v115, v44, v115
	v_add_f32_e32 v115, v45, v115
	s_waitcnt lgkmcnt(4)
	v_mfma_f32_32x32x16_bf16 v[2:17], v[172:175], v[160:163], v[2:17]
	v_add_f32_e32 v164, v46, v164
	v_add_f32_e32 v164, v47, v164
	v_add_f32_e32 v164, v48, v164
	v_add_f32_e32 v164, v49, v164
	s_waitcnt lgkmcnt(2)
	v_mfma_f32_32x32x16_bf16 v[18:33], v[176:179], v[184:187], v[18:33]
	s_waitcnt lgkmcnt(0)
	v_mfma_f32_32x32x16_bf16 v[2:17], v[180:183], v[184:187], v[2:17]
	s_waitcnt lgkmcnt(0)
	s_barrier
	s_add_i32 s38, s38, 1
	s_cmp_ge_u32 s38, s96
	s_cbranch_scc1 .Lds0_done
	ds_read_b128 v[106:109], v0 offset:32768
	ds_read_b128 v[110:113], v102 offset:32768
	ds_read_b128 v[120:123], v103 offset:32768
	ds_read_b128 v[124:127], v104 offset:32768
	ds_read_b64_tr_b16 v[168:169], v98 offset:24576
	ds_read_b64_tr_b16 v[170:171], v98 offset:24832
	ds_read_b64_tr_b16 v[172:173], v98 offset:25088
	ds_read_b64_tr_b16 v[174:175], v98 offset:25344
	ds_read_b64_tr_b16 v[176:177], v98 offset:26624
	ds_read_b64_tr_b16 v[178:179], v98 offset:26880
	ds_read_b64_tr_b16 v[180:181], v98 offset:27136
	ds_read_b64_tr_b16 v[182:183], v98 offset:27392
	s_waitcnt vmcnt(0)
	ds_write_b128 v100, v[82:85] offset:0
	ds_write_b128 v165, v[86:89] offset:8192
	s_add_i32 s39, s38, 3
	s_cmp_lt_u32 s39, s96
	s_cbranch_scc0 .Lds0_sk1
	global_load_dwordx4 v[82:85], v[92:93], off offset:1024
	global_load_dwordx4 v[86:89], v[90:91], off offset:1280
	v_lshl_add_u64 v[92:93], v[92:93], 0, s[70:71]
	v_lshl_add_u64 v[90:91], v[90:91], 0, s[70:71]
; template <int DV, int NK, int MODE, bool FIXM, int GRP>
; DI void attn_job(char* lds_wg, const AttnJob& J) {
;     ...
;       if (NDV == 2 || FIXM) {
;         bf16x8 ka[4], kb[4];
; #pragma unroll
;         for (int ds = 0; ds < 4; ++ds) { const int co = ((2 * ds + h) ^ ((r >> 1) & 7)) << 4; ka[ds] = *(const bf16x8*)(Kl + co); kb[ds] = *(const bf16x8*)(Kl + 4096 + co); }
; #pragma unroll
;         for (int ds = 0; ds < 4; ++ds) { sA = MFMA32(ka[ds], qf[ds], sA); sB = MFMA32(kb[ds], qf[ds], sB); }
;         __builtin_amdgcn_sched_group_barrier(0x100, 4, 0); __builtin_amdgcn_sched_group_barrier(0x008, 2, 0);
;         __builtin_amdgcn_sched_group_barrier(0x100, 2, 0); __builtin_amdgcn_sched_group_barrier(0x008, 2, 0);
;         __builtin_amdgcn_sched_group_barrier(0x100, 2, 0); __builtin_amdgcn_sched_group_barrier(0x008, 4, 0);
;       } else {
; #pragma unroll
;         for (int ds = 0; ds < 4; ++ds) {
;           const int co = ((2 * ds + h) ^ ((r >> 1) & 7)) << 4;
;           const bf16x8 ka = *(const bf16x8*)(Kl + co), kb = *(const bf16x8*)(Kl + 4096 + co);
;           sA = MFMA32(ka, qf[ds], sA); sB = MFMA32(kb, qf[ds], sB);
;         }
;       }
;       if (MODE == AM_SWA) {
;         const int qa = J.qpos0 + r, kbase = tile * 64 + 8 * h;
; #pragma unroll
;         for (int i = 0; i < 16; ++i) {
;           const int ka_ = kbase + 16 * (i >> 3) + (i & 7);
;           int d0 = qa - ka_; d0 = d0 < 0 ? -d0 : d0; if (d0 > 128) sA[i] = -INFINITY;
;           int d1 = qa - (ka_ + 32); d1 = d1 < 0 ? -d1 : d1; if (d1 > 128) sB[i] = -INFINITY;
;         }
;       }
;       if (FIXM) {
;         const float nm = -J.m_init;
; #pragma unroll
;         for (int i = 0; i < 16; ++i) { sA[i] = __builtin_amdgcn_exp2f(fmaf(sA[i], C, nm)); sB[i] = __builtin_amdgcn_exp2f(fmaf(sB[i], C, nm)); l += sA[i] + sB[i]; }
;     ...
;       bf16x8 pf[4];
;       { u32x4 w;
;         w.x = cvtpk(sA[0], sA[1]); w.y = cvtpk(sA[2], sA[3]); w.z = cvtpk(sA[4], sA[5]); w.w = cvtpk(sA[6], sA[7]); pf[0] = __builtin_bit_cast(bf16x8, w);
;         w.x = cvtpk(sA[8], sA[9]); w.y = cvtpk(sA[10], sA[11]); w.z = cvtpk(sA[12], sA[13]); w.w = cvtpk(sA[14], sA[15]); pf[1] = __builtin_bit_cast(bf16x8, w);
;         w.x = cvtpk(sB[0], sB[1]); w.y = cvtpk(sB[2], sB[3]); w.z = cvtpk(sB[4], sB[5]); w.w = cvtpk(sB[6], sB[7]); pf[2] = __builtin_bit_cast(bf16x8, w);
.Lds0_sk1:
	v_exp_f32_e32 v136, v136
	v_exp_f32_e32 v137, v137
	v_exp_f32_e32 v138, v138
	v_exp_f32_e32 v139, v139
	v_exp_f32_e32 v140, v140
	v_exp_f32_e32 v141, v141
	v_exp_f32_e32 v142, v142
	v_exp_f32_e32 v143, v143
	s_waitcnt lgkmcnt(13)
	v_mfma_f32_32x32x16_bf16 v[34:49], v[106:109], v[66:69], 0
	v_cvt_pk_bf16_f32 v152, v136, v137
	v_cvt_pk_bf16_f32 v153, v138, v139
	v_cvt_pk_bf16_f32 v154, v140, v141
	v_cvt_pk_bf16_f32 v155, v142, v143
	v_add_f32_e32 v115, v136, v115
	v_add_f32_e32 v115, v137, v115
	s_waitcnt lgkmcnt(12)
	v_mfma_f32_32x32x16_bf16 v[34:49], v[110:113], v[70:73], v[34:49]
	v_exp_f32_e32 v144, v144
	v_exp_f32_e32 v145, v145
	v_exp_f32_e32 v146, v146
	v_exp_f32_e32 v147, v147
	v_add_f32_e32 v164, v138, v164
	v_add_f32_e32 v164, v139, v164
	s_waitcnt lgkmcnt(11)
	v_mfma_f32_32x32x16_bf16 v[34:49], v[120:123], v[74:77], v[34:49]
	v_exp_f32_e32 v148, v148
	v_exp_f32_e32 v149, v149
	v_exp_f32_e32 v150, v150
	v_exp_f32_e32 v151, v151
	v_add_f32_e32 v115, v140, v115
	v_add_f32_e32 v115, v141, v115
	s_waitcnt lgkmcnt(10)
	v_mfma_f32_32x32x16_bf16 v[34:49], v[124:127], v[78:81], v[34:49]
	ds_read_b128 v[106:109], v0 offset:36864
	ds_read_b128 v[110:113], v102 offset:36864
	ds_read_b128 v[120:123], v103 offset:36864
	ds_read_b128 v[124:127], v104 offset:36864
	v_add_f32_e32 v164, v142, v164
	v_add_f32_e32 v164, v143, v164
	s_waitcnt lgkmcnt(12)
	v_mfma_f32_32x32x16_bf16 v[18:33], v[168:171], v[152:155], v[18:33]
	v_cvt_pk_bf16_f32 v156, v144, v145
	v_cvt_pk_bf16_f32 v157, v146, v147
	v_cvt_pk_bf16_f32 v158, v148, v149
	v_cvt_pk_bf16_f32 v159, v150, v151
	v_add_f32_e32 v115, v144, v115
	v_add_f32_e32 v115, v145, v115
	s_waitcnt lgkmcnt(10)
	v_mfma_f32_32x32x16_bf16 v[2:17], v[172:175], v[152:155], v[2:17]
	v_add_f32_e32 v164, v146, v164
	v_add_f32_e32 v164, v147, v164
	v_add_f32_e32 v164, v148, v164
	v_add_f32_e32 v164, v149, v164
	v_add_f32_e32 v164, v150, v164
	v_add_f32_e32 v164, v151, v164
	s_waitcnt lgkmcnt(8)
	v_mfma_f32_32x32x16_bf16 v[18:33], v[176:179], v[156:159], v[18:33]
	v_exp_f32_e32 v50, v50
	v_exp_f32_e32 v51, v51
	v_exp_f32_e32 v52, v52
	v_exp_f32_e32 v53, v53
	s_waitcnt lgkmcnt(6)
	v_mfma_f32_32x32x16_bf16 v[2:17], v[180:183], v[156:159], v[2:17]
	ds_read_b64_tr_b16 v[168:169], v98 offset:28672
	ds_read_b64_tr_b16 v[170:171], v98 offset:28928
	ds_read_b64_tr_b16 v[172:173], v98 offset:29184
	ds_read_b64_tr_b16 v[174:175], v98 offset:29440
	ds_read_b64_tr_b16 v[176:177], v98 offset:30720
	ds_read_b64_tr_b16 v[178:179], v98 offset:30976
	ds_read_b64_tr_b16 v[180:181], v98 offset:31232
	ds_read_b64_tr_b16 v[182:183], v98 offset:31488
	v_exp_f32_e32 v54, v54
	v_exp_f32_e32 v55, v55
	v_exp_f32_e32 v56, v56
	v_exp_f32_e32 v57, v57
	s_waitcnt lgkmcnt(11)
	v_mfma_f32_32x32x16_bf16 v[136:151], v[106:109], v[66:69], 0
	v_cvt_pk_bf16_f32 v160, v50, v51
	v_cvt_pk_bf16_f32 v161, v52, v53
	v_cvt_pk_bf16_f32 v162, v54, v55
	v_cvt_pk_bf16_f32 v163, v56, v57
	v_add_f32_e32 v115, v50, v115
	v_add_f32_e32 v115, v51, v115
	s_waitcnt lgkmcnt(10)
	v_mfma_f32_32x32x16_bf16 v[136:151], v[110:113], v[70:73], v[136:151]
	v_exp_f32_e32 v58, v58
	v_exp_f32_e32 v59, v59
	v_exp_f32_e32 v60, v60
	v_exp_f32_e32 v61, v61
	v_add_f32_e32 v164, v52, v164
	v_add_f32_e32 v164, v53, v164
	s_waitcnt lgkmcnt(9)
	v_mfma_f32_32x32x16_bf16 v[136:151], v[120:123], v[74:77], v[136:151]
	v_exp_f32_e32 v62, v62
	v_exp_f32_e32 v63, v63
	v_exp_f32_e32 v64, v64
	v_exp_f32_e32 v65, v65
	v_add_f32_e32 v115, v54, v115
	v_add_f32_e32 v115, v55, v115
	s_waitcnt lgkmcnt(8)
	v_mfma_f32_32x32x16_bf16 v[136:151], v[124:127], v[78:81], v[136:151]
	v_cvt_pk_bf16_f32 v184, v58, v59
	v_cvt_pk_bf16_f32 v185, v60, v61
	v_cvt_pk_bf16_f32 v186, v62, v63
	v_cvt_pk_bf16_f32 v187, v64, v65
	v_add_f32_e32 v164, v56, v164
	v_add_f32_e32 v164, v57, v164
	s_waitcnt lgkmcnt(6)
	v_mfma_f32_32x32x16_bf16 v[18:33], v[168:171], v[160:163], v[18:33]
	v_add_f32_e32 v115, v58, v115
	v_add_f32_e32 v115, v59, v115
	v_add_f32_e32 v115, v60, v115
	v_add_f32_e32 v115, v61, v115
	s_waitcnt lgkmcnt(4)
	v_mfma_f32_32x32x16_bf16 v[2:17], v[172:175], v[160:163], v[2:17]
	v_add_f32_e32 v164, v62, v164
	v_add_f32_e32 v164, v63, v164
	v_add_f32_e32 v164, v64, v164
	v_add_f32_e32 v164, v65, v164
	s_waitcnt lgkmcnt(2)
	v_mfma_f32_32x32x16_bf16 v[18:33], v[176:179], v[184:187], v[18:33]
	s_waitcnt lgkmcnt(0)
	v_mfma_f32_32x32x16_bf16 v[2:17], v[180:183], v[184:187], v[2:17]
	s_waitcnt lgkmcnt(0)
	s_barrier
	s_add_i32 s38, s38, 1
	s_cmp_ge_u32 s38, s96
	s_cbranch_scc1 .Lds0_done
	ds_read_b128 v[106:109], v0 offset:0
	ds_read_b128 v[110:113], v102 offset:0
	ds_read_b128 v[120:123], v103 offset:0
	ds_read_b128 v[124:127], v104 offset:0
	ds_read_b64_tr_b16 v[168:169], v98 offset:40960
	ds_read_b64_tr_b16 v[170:171], v98 offset:41216
	ds_read_b64_tr_b16 v[172:173], v98 offset:41472
	ds_read_b64_tr_b16 v[174:175], v98 offset:41728
	ds_read_b64_tr_b16 v[176:177], v98 offset:43008
	ds_read_b64_tr_b16 v[178:179], v98 offset:43264
	ds_read_b64_tr_b16 v[180:181], v98 offset:43520
	ds_read_b64_tr_b16 v[182:183], v98 offset:43776
	s_waitcnt vmcnt(0)
	ds_write_b128 v100, v[82:85] offset:16384
	ds_write_b128 v165, v[86:89] offset:24576
	s_add_i32 s39, s38, 3
	s_cmp_lt_u32 s39, s96
	s_cbranch_scc0 .Lds0_sk2
	global_load_dwordx4 v[82:85], v[92:93], off offset:1024
	global_load_dwordx4 v[86:89], v[90:91], off offset:1280
	v_lshl_add_u64 v[92:93], v[92:93], 0, s[70:71]
	v_lshl_add_u64 v[90:91], v[90:91], 0, s[70:71]
; template <int DV, int NK, int MODE, bool FIXM, int GRP>
; DI void attn_job(char* lds_wg, const AttnJob& J) {
;     ...
;       if (NDV == 2 || FIXM) {
;         bf16x8 ka[4], kb[4];
; #pragma unroll
;         for (int ds = 0; ds < 4; ++ds) { const int co = ((2 * ds + h) ^ ((r >> 1) & 7)) << 4; ka[ds] = *(const bf16x8*)(Kl + co); kb[ds] = *(const bf16x8*)(Kl + 4096 + co); }
; #pragma unroll
;         for (int ds = 0; ds < 4; ++ds) { sA = MFMA32(ka[ds], qf[ds], sA); sB = MFMA32(kb[ds], qf[ds], sB); }
;         __builtin_amdgcn_sched_group_barrier(0x100, 4, 0); __builtin_amdgcn_sched_group_barrier(0x008, 2, 0);
;         __builtin_amdgcn_sched_group_barrier(0x100, 2, 0); __builtin_amdgcn_sched_group_barrier(0x008, 2, 0);
;         __builtin_amdgcn_sched_group_barrier(0x100, 2, 0); __builtin_amdgcn_sched_group_barrier(0x008, 4, 0);
;       } else {
; #pragma unroll
;         for (int ds = 0; ds < 4; ++ds) {
;           const int co = ((2 * ds + h) ^ ((r >> 1) & 7)) << 4;
;           const bf16x8 ka = *(const bf16x8*)(Kl + co), kb = *(const bf16x8*)(Kl + 4096 + co);
;           sA = MFMA32(ka, qf[ds], sA); sB = MFMA32(kb, qf[ds], sB);
;         }
;       }
;       if (MODE == AM_SWA) {
;         const int qa = J.qpos0 + r, kbase = tile * 64 + 8 * h;
; #pragma unroll
;         for (int i = 0; i < 16; ++i) {
;           const int ka_ = kbase + 16 * (i >> 3) + (i & 7);
;           int d0 = qa - ka_; d0 = d0 < 0 ? -d0 : d0; if (d0 > 128) sA[i] = -INFINITY;
;           int d1 = qa - (ka_ + 32); d1 = d1 < 0 ? -d1 : d1; if (d1 > 128) sB[i] = -INFINITY;
;         }
;       }
;       if (FIXM) {
;         const float nm = -J.m_init;
; #pragma unroll
;         for (int i = 0; i < 16; ++i) { sA[i] = __builtin_amdgcn_exp2f(fmaf(sA[i], C, nm)); sB[i] = __builtin_amdgcn_exp2f(fmaf(sB[i], C, nm)); l += sA[i] + sB[i]; }
;     ...
;       bf16x8 pf[4];
;       { u32x4 w;
;         w.x = cvtpk(sA[0], sA[1]); w.y = cvtpk(sA[2], sA[3]); w.z = cvtpk(sA[4], sA[5]); w.w = cvtpk(sA[6], sA[7]); pf[0] = __builtin_bit_cast(bf16x8, w);
;         w.x = cvtpk(sA[8], sA[9]); w.y = cvtpk(sA[10], sA[11]); w.z = cvtpk(sA[12], sA[13]); w.w = cvtpk(sA[14], sA[15]); pf[1] = __builtin_bit_cast(bf16x8, w);
;         w.x = cvtpk(sB[0], sB[1]); w.y = cvtpk(sB[2], sB[3]); w.z = cvtpk(sB[4], sB[5]); w.w = cvtpk(sB[6], sB[7]); pf[2] = __builtin_bit_cast(bf16x8, w);
.Lds0_sk2:
	v_exp_f32_e32 v34, v34
	v_exp_f32_e32 v35, v35
	v_exp_f32_e32 v36, v36
	v_exp_f32_e32 v37, v37
	v_exp_f32_e32 v38, v38
	v_exp_f32_e32 v39, v39
	v_exp_f32_e32 v40, v40
	v_exp_f32_e32 v41, v41
	s_waitcnt lgkmcnt(13)
	v_mfma_f32_32x32x16_bf16 v[50:65], v[106:109], v[66:69], 0
	v_cvt_pk_bf16_f32 v152, v34, v35
	v_cvt_pk_bf16_f32 v153, v36, v37
	v_cvt_pk_bf16_f32 v154, v38, v39
	v_cvt_pk_bf16_f32 v155, v40, v41
	v_add_f32_e32 v115, v34, v115
	v_add_f32_e32 v115, v35, v115
	s_waitcnt lgkmcnt(12)
	v_mfma_f32_32x32x16_bf16 v[50:65], v[110:113], v[70:73], v[50:65]
	v_exp_f32_e32 v42, v42
	v_exp_f32_e32 v43, v43
	v_exp_f32_e32 v44, v44
	v_exp_f32_e32 v45, v45
	v_add_f32_e32 v164, v36, v164
	v_add_f32_e32 v164, v37, v164
	s_waitcnt lgkmcnt(11)
	v_mfma_f32_32x32x16_bf16 v[50:65], v[120:123], v[74:77], v[50:65]
	v_exp_f32_e32 v46, v46
	v_exp_f32_e32 v47, v47
	v_exp_f32_e32 v48, v48
	v_exp_f32_e32 v49, v49
	v_add_f32_e32 v115, v38, v115
	v_add_f32_e32 v115, v39, v115
	s_waitcnt lgkmcnt(10)
	v_mfma_f32_32x32x16_bf16 v[50:65], v[124:127], v[78:81], v[50:65]
	ds_read_b128 v[106:109], v0 offset:4096
	ds_read_b128 v[110:113], v102 offset:4096
	ds_read_b128 v[120:123], v103 offset:4096
	ds_read_b128 v[124:127], v104 offset:4096
	v_add_f32_e32 v164, v40, v164
	v_add_f32_e32 v164, v41, v164
	s_waitcnt lgkmcnt(12)
	v_mfma_f32_32x32x16_bf16 v[18:33], v[168:171], v[152:155], v[18:33]
	v_cvt_pk_bf16_f32 v156, v42, v43
	v_cvt_pk_bf16_f32 v157, v44, v45
	v_cvt_pk_bf16_f32 v158, v46, v47
	v_cvt_pk_bf16_f32 v159, v48, v49
	v_add_f32_e32 v115, v42, v115
	v_add_f32_e32 v115, v43, v115
	s_waitcnt lgkmcnt(10)
	v_mfma_f32_32x32x16_bf16 v[2:17], v[172:175], v[152:155], v[2:17]
	v_add_f32_e32 v164, v44, v164
	v_add_f32_e32 v164, v45, v164
	v_add_f32_e32 v164, v46, v164
	v_add_f32_e32 v164, v47, v164
	v_add_f32_e32 v164, v48, v164
	v_add_f32_e32 v164, v49, v164
	s_waitcnt lgkmcnt(8)
	v_mfma_f32_32x32x16_bf16 v[18:33], v[176:179], v[156:159], v[18:33]
	v_exp_f32_e32 v136, v136
	v_exp_f32_e32 v137, v137
	v_exp_f32_e32 v138, v138
	v_exp_f32_e32 v139, v139
	s_waitcnt lgkmcnt(6)
	v_mfma_f32_32x32x16_bf16 v[2:17], v[180:183], v[156:159], v[2:17]
	ds_read_b64_tr_b16 v[168:169], v98 offset:45056
	ds_read_b64_tr_b16 v[170:171], v98 offset:45312
	ds_read_b64_tr_b16 v[172:173], v98 offset:45568
	ds_read_b64_tr_b16 v[174:175], v98 offset:45824
	ds_read_b64_tr_b16 v[176:177], v98 offset:47104
	ds_read_b64_tr_b16 v[178:179], v98 offset:47360
	ds_read_b64_tr_b16 v[180:181], v98 offset:47616
	ds_read_b64_tr_b16 v[182:183], v98 offset:47872
	v_exp_f32_e32 v140, v140
	v_exp_f32_e32 v141, v141
	v_exp_f32_e32 v142, v142
	v_exp_f32_e32 v143, v143
	s_waitcnt lgkmcnt(11)
	v_mfma_f32_32x32x16_bf16 v[34:49], v[106:109], v[66:69], 0
	v_cvt_pk_bf16_f32 v160, v136, v137
	v_cvt_pk_bf16_f32 v161, v138, v139
	v_cvt_pk_bf16_f32 v162, v140, v141
	v_cvt_pk_bf16_f32 v163, v142, v143
	v_add_f32_e32 v115, v136, v115
	v_add_f32_e32 v115, v137, v115
	s_waitcnt lgkmcnt(10)
	v_mfma_f32_32x32x16_bf16 v[34:49], v[110:113], v[70:73], v[34:49]
	v_exp_f32_e32 v144, v144
	v_exp_f32_e32 v145, v145
	v_exp_f32_e32 v146, v146
	v_exp_f32_e32 v147, v147
	v_add_f32_e32 v164, v138, v164
	v_add_f32_e32 v164, v139, v164
	s_waitcnt lgkmcnt(9)
	v_mfma_f32_32x32x16_bf16 v[34:49], v[120:123], v[74:77], v[34:49]
	v_exp_f32_e32 v148, v148
	v_exp_f32_e32 v149, v149
	v_exp_f32_e32 v150, v150
	v_exp_f32_e32 v151, v151
	v_add_f32_e32 v115, v140, v115
	v_add_f32_e32 v115, v141, v115
	s_waitcnt lgkmcnt(8)
	v_mfma_f32_32x32x16_bf16 v[34:49], v[124:127], v[78:81], v[34:49]
	v_cvt_pk_bf16_f32 v184, v144, v145
	v_cvt_pk_bf16_f32 v185, v146, v147
	v_cvt_pk_bf16_f32 v186, v148, v149
	v_cvt_pk_bf16_f32 v187, v150, v151
	v_add_f32_e32 v164, v142, v164
	v_add_f32_e32 v164, v143, v164
	s_waitcnt lgkmcnt(6)
	v_mfma_f32_32x32x16_bf16 v[18:33], v[168:171], v[160:163], v[18:33]
	v_add_f32_e32 v115, v144, v115
	v_add_f32_e32 v115, v145, v115
	v_add_f32_e32 v115, v146, v115
	v_add_f32_e32 v115, v147, v115
	s_waitcnt lgkmcnt(4)
	v_mfma_f32_32x32x16_bf16 v[2:17], v[172:175], v[160:163], v[2:17]
	v_add_f32_e32 v164, v148, v164
	v_add_f32_e32 v164, v149, v164
	v_add_f32_e32 v164, v150, v164
	v_add_f32_e32 v164, v151, v164
	s_waitcnt lgkmcnt(2)
	v_mfma_f32_32x32x16_bf16 v[18:33], v[176:179], v[184:187], v[18:33]
	s_waitcnt lgkmcnt(0)
	v_mfma_f32_32x32x16_bf16 v[2:17], v[180:183], v[184:187], v[2:17]
	s_waitcnt lgkmcnt(0)
	s_barrier
	s_add_i32 s38, s38, 1
	s_cmp_ge_u32 s38, s96
	s_cbranch_scc1 .Lds0_done
	s_branch .Lds0_loop
.Lds0_done:
	v_add_f32_e32 v115, v115, v164
	s_branch .LBB0_272

; #define MFMA32(a, b, c) __builtin_amdgcn_mfma_f32_32x32x16_bf16((a), (b), (c), 0, 0, 0)
; #define A_LOAD(t, rk, rv) do { const size_t kb_ = (size_t)(t) * 64; \
;     _Pragma("unroll") for (int s = 0; s < NK; ++s) _Pragma("unroll") for (int i = 0; i < KI; ++i) rk[s][i] = *(const u32x4*)(J.k[s] + (kb_ + ksrow + 32 * i) * J.ldk + ksch * 8); \
;     _Pragma("unroll") for (int i = 0; i < VI; ++i) rv[i] = *(const u32x4*)(J.v + (kb_ + vkey0 + (STN / VCH) * i) * J.ldv + vc8); } while (0)
; template <int DV, int NK, int MODE, bool FIXM, int GRP>
; DI void attn_job(char* lds_wg, const AttnJob& J) {
;     ...
;   bf16x8 qf[4];
;   const bf16_t* qrow = J.q + (size_t)r * UW + 8 * h;
; #pragma unroll
;   for (int ds = 0; ds < 4; ++ds) qf[ds] = *(const bf16x8*)(qrow + 16 * ds);
;     ...
;   A_LOAD(J.tile_lo, rk0, rv0); A_WRITE(0, rk0, rv0); if (ONESET) A_LOAD(J.tile_lo + 1, rk0, rv0); else if (DEEP2) A_LOAD(J.tile_lo + 1, rk1, rv1); __syncthreads();
;   const int i16 = lane & 15;
;   const int vrd = h * NDV * 512 + (i16 >> 2) * 64 + (((lane >> 4) & 1) * 16 + (i16 & 3) * 4) * 2;
;   auto compute = [&](const int stage, const int tile) __attribute__((always_inline)) {
;     bool active = true;
;     if (MODE == AM_SWA) { const int k0 = tile * 64; active = !(k0 > J.qpos0 + 31 + 128 || k0 + 63 < J.qpos0 - 128); }
;     if (active) {
;       const char* Kl = lds + stage * 32768 + kstream * 8192 + r * 128;
;       f32x16 sA, sB;
; #pragma unroll
;       for (int i = 0; i < 16; ++i) { sA[i] = 0.f; sB[i] = 0.f; }
;       if (NDV == 2 || FIXM) {
;         bf16x8 ka[4], kb[4];
; #pragma unroll
;         for (int ds = 0; ds < 4; ++ds) { const int co = ((2 * ds + h) ^ ((r >> 1) & 7)) << 4; ka[ds] = *(const bf16x8*)(Kl + co); kb[ds] = *(const bf16x8*)(Kl + 4096 + co); }
; #pragma unroll
;         for (int ds = 0; ds < 4; ++ds) { sA = MFMA32(ka[ds], qf[ds], sA); sB = MFMA32(kb[ds], qf[ds], sB); }
.Lds1_entry:
	s_waitcnt vmcnt(2)
	v_lshlrev_b32_e32 v34, 16, v66
	v_and_b32_e32 v35, 0xffff0000, v66
	v_mul_f32_e32 v34, s7, v34
	v_mul_f32_e32 v35, s7, v35
	v_cvt_pk_bf16_f32 v66, v34, v35
	v_lshlrev_b32_e32 v34, 16, v67
	v_and_b32_e32 v35, 0xffff0000, v67
	v_mul_f32_e32 v34, s7, v34
	v_mul_f32_e32 v35, s7, v35
	v_cvt_pk_bf16_f32 v67, v34, v35
	v_lshlrev_b32_e32 v34, 16, v68
	v_and_b32_e32 v35, 0xffff0000, v68
	v_mul_f32_e32 v34, s7, v34
	v_mul_f32_e32 v35, s7, v35
	v_cvt_pk_bf16_f32 v68, v34, v35
	v_lshlrev_b32_e32 v34, 16, v69
	v_and_b32_e32 v35, 0xffff0000, v69
	v_mul_f32_e32 v34, s7, v34
	v_mul_f32_e32 v35, s7, v35
	v_cvt_pk_bf16_f32 v69, v34, v35
	v_lshlrev_b32_e32 v34, 16, v70
	v_and_b32_e32 v35, 0xffff0000, v70
	v_mul_f32_e32 v34, s7, v34
	v_mul_f32_e32 v35, s7, v35
	v_cvt_pk_bf16_f32 v70, v34, v35
	v_lshlrev_b32_e32 v34, 16, v71
	v_and_b32_e32 v35, 0xffff0000, v71
	v_mul_f32_e32 v34, s7, v34
	v_mul_f32_e32 v35, s7, v35
	v_cvt_pk_bf16_f32 v71, v34, v35
	v_lshlrev_b32_e32 v34, 16, v72
	v_and_b32_e32 v35, 0xffff0000, v72
	v_mul_f32_e32 v34, s7, v34
	v_mul_f32_e32 v35, s7, v35
	v_cvt_pk_bf16_f32 v72, v34, v35
	v_lshlrev_b32_e32 v34, 16, v73
	v_and_b32_e32 v35, 0xffff0000, v73
	v_mul_f32_e32 v34, s7, v34
	v_mul_f32_e32 v35, s7, v35
	v_cvt_pk_bf16_f32 v73, v34, v35
	v_lshlrev_b32_e32 v34, 16, v74
	v_and_b32_e32 v35, 0xffff0000, v74
	v_mul_f32_e32 v34, s7, v34
	v_mul_f32_e32 v35, s7, v35
	v_cvt_pk_bf16_f32 v74, v34, v35
	v_lshlrev_b32_e32 v34, 16, v75
	v_and_b32_e32 v35, 0xffff0000, v75
	v_mul_f32_e32 v34, s7, v34
	v_mul_f32_e32 v35, s7, v35
	v_cvt_pk_bf16_f32 v75, v34, v35
	v_lshlrev_b32_e32 v34, 16, v76
	v_and_b32_e32 v35, 0xffff0000, v76
	v_mul_f32_e32 v34, s7, v34
	v_mul_f32_e32 v35, s7, v35
	v_cvt_pk_bf16_f32 v76, v34, v35
	v_lshlrev_b32_e32 v34, 16, v77
	v_and_b32_e32 v35, 0xffff0000, v77
	v_mul_f32_e32 v34, s7, v34
	v_mul_f32_e32 v35, s7, v35
	v_cvt_pk_bf16_f32 v77, v34, v35
	v_lshlrev_b32_e32 v34, 16, v78
	v_and_b32_e32 v35, 0xffff0000, v78
	v_mul_f32_e32 v34, s7, v34
	v_mul_f32_e32 v35, s7, v35
	v_cvt_pk_bf16_f32 v78, v34, v35
	v_lshlrev_b32_e32 v34, 16, v79
	v_and_b32_e32 v35, 0xffff0000, v79
	v_mul_f32_e32 v34, s7, v34
	v_mul_f32_e32 v35, s7, v35
	v_cvt_pk_bf16_f32 v79, v34, v35
	v_lshlrev_b32_e32 v34, 16, v80
	v_and_b32_e32 v35, 0xffff0000, v80
	v_mul_f32_e32 v34, s7, v34
	v_mul_f32_e32 v35, s7, v35
	v_cvt_pk_bf16_f32 v80, v34, v35
	v_lshlrev_b32_e32 v34, 16, v81
	v_and_b32_e32 v35, 0xffff0000, v81
	v_mul_f32_e32 v34, s7, v34
	v_mul_f32_e32 v35, s7, v35
	v_cvt_pk_bf16_f32 v81, v34, v35
	v_add_u32_e32 v165, v101, v99
	s_mov_b32 s10, 0x78000
	s_mov_b32 s11, 0
	v_lshl_add_u64 v[92:93], v[92:93], 0, s[14:15]
	v_lshl_add_u64 v[90:91], v[90:91], 0, s[14:15]
	v_lshl_add_u64 v[92:93], v[92:93], 0, s[94:95]
	v_lshl_add_u64 v[90:91], v[90:91], 0, s[94:95]
	ds_read_b128 v[106:109], v0
	ds_read_b128 v[110:113], v102
	ds_read_b128 v[120:123], v103
	ds_read_b128 v[124:127], v104
	s_waitcnt vmcnt(0)
	ds_write_b128 v100, v[82:85] offset:16384
	ds_write_b128 v165, v[86:89] offset:24576
	global_load_dwordx4 v[82:85], v[92:93], off offset:1024
	global_load_dwordx4 v[86:89], v[90:91], off offset:1280
	v_lshl_add_u64 v[92:93], v[92:93], 0, s[10:11]
	v_lshl_add_u64 v[90:91], v[90:91], 0, s[10:11]
	s_waitcnt lgkmcnt(5)
	v_mfma_f32_32x32x16_bf16 v[50:65], v[106:109], v[66:69], 0
	s_waitcnt lgkmcnt(4)
	v_mfma_f32_32x32x16_bf16 v[50:65], v[110:113], v[70:73], v[50:65]
	s_waitcnt lgkmcnt(3)
	v_mfma_f32_32x32x16_bf16 v[50:65], v[120:123], v[74:77], v[50:65]
	s_waitcnt lgkmcnt(2)
	v_mfma_f32_32x32x16_bf16 v[50:65], v[124:127], v[78:81], v[50:65]
	ds_read_b128 v[106:109], v0 offset:4096
	ds_read_b128 v[110:113], v102 offset:4096
	ds_read_b128 v[120:123], v103 offset:4096
	ds_read_b128 v[124:127], v104 offset:4096
	s_waitcnt lgkmcnt(3)
	v_mfma_f32_32x32x16_bf16 v[34:49], v[106:109], v[66:69], 0
	s_waitcnt lgkmcnt(2)
	v_mfma_f32_32x32x16_bf16 v[34:49], v[110:113], v[70:73], v[34:49]
	s_waitcnt lgkmcnt(1)
	v_mfma_f32_32x32x16_bf16 v[34:49], v[120:123], v[74:77], v[34:49]
	s_waitcnt lgkmcnt(0)
	v_mfma_f32_32x32x16_bf16 v[34:49], v[124:127], v[78:81], v[34:49]
	v_mov_b32_e32 v164, 0
	s_mov_b32 s30, 0
	s_waitcnt lgkmcnt(0)
	s_barrier
.Lds1_loop:
	ds_read_b128 v[106:109], v0 offset:16384
	ds_read_b128 v[110:113], v102 offset:16384
	ds_read_b128 v[120:123], v103 offset:16384
	ds_read_b128 v[124:127], v104 offset:16384
	ds_read_b64_tr_b16 v[168:169], v98 offset:8192
	ds_read_b64_tr_b16 v[170:171], v98 offset:8448
	ds_read_b64_tr_b16 v[172:173], v98 offset:8704
	ds_read_b64_tr_b16 v[174:175], v98 offset:8960
	ds_read_b64_tr_b16 v[176:177], v98 offset:10240
	ds_read_b64_tr_b16 v[178:179], v98 offset:10496
	ds_read_b64_tr_b16 v[180:181], v98 offset:10752
	ds_read_b64_tr_b16 v[182:183], v98 offset:11008
	s_waitcnt vmcnt(0)
	ds_write_b128 v100, v[82:85] offset:32768
	ds_write_b128 v165, v[86:89] offset:40960
	s_add_i32 s31, s30, 3
	s_cmp_lt_u32 s31, s96
	s_cbranch_scc0 .Lds1_sk0
	global_load_dwordx4 v[82:85], v[92:93], off offset:1024
	global_load_dwordx4 v[86:89], v[90:91], off offset:1280
	v_lshl_add_u64 v[92:93], v[92:93], 0, s[10:11]
	v_lshl_add_u64 v[90:91], v[90:91], 0, s[10:11]
; template <int DV, int NK, int MODE, bool FIXM, int GRP>
; DI void attn_job(char* lds_wg, const AttnJob& J) {
;     ...
;       if (NDV == 2 || FIXM) {
;         bf16x8 ka[4], kb[4];
; #pragma unroll
;         for (int ds = 0; ds < 4; ++ds) { const int co = ((2 * ds + h) ^ ((r >> 1) & 7)) << 4; ka[ds] = *(const bf16x8*)(Kl + co); kb[ds] = *(const bf16x8*)(Kl + 4096 + co); }
; #pragma unroll
;         for (int ds = 0; ds < 4; ++ds) { sA = MFMA32(ka[ds], qf[ds], sA); sB = MFMA32(kb[ds], qf[ds], sB); }
;         __builtin_amdgcn_sched_group_barrier(0x100, 4, 0); __builtin_amdgcn_sched_group_barrier(0x008, 2, 0);
;         __builtin_amdgcn_sched_group_barrier(0x100, 2, 0); __builtin_amdgcn_sched_group_barrier(0x008, 2, 0);
;         __builtin_amdgcn_sched_group_barrier(0x100, 2, 0); __builtin_amdgcn_sched_group_barrier(0x008, 4, 0);
;       } else {
; #pragma unroll
;         for (int ds = 0; ds < 4; ++ds) {
;           const int co = ((2 * ds + h) ^ ((r >> 1) & 7)) << 4;
;           const bf16x8 ka = *(const bf16x8*)(Kl + co), kb = *(const bf16x8*)(Kl + 4096 + co);
;           sA = MFMA32(ka, qf[ds], sA); sB = MFMA32(kb, qf[ds], sB);
;         }
;       }
;       if (MODE == AM_SWA) {
;         const int qa = J.qpos0 + r, kbase = tile * 64 + 8 * h;
; #pragma unroll
;         for (int i = 0; i < 16; ++i) {
;           const int ka_ = kbase + 16 * (i >> 3) + (i & 7);
;           int d0 = qa - ka_; d0 = d0 < 0 ? -d0 : d0; if (d0 > 128) sA[i] = -INFINITY;
;           int d1 = qa - (ka_ + 32); d1 = d1 < 0 ? -d1 : d1; if (d1 > 128) sB[i] = -INFINITY;
;         }
;       }
;       if (FIXM) {
;         const float nm = -J.m_init;
; #pragma unroll
;         for (int i = 0; i < 16; ++i) { sA[i] = __builtin_amdgcn_exp2f(fmaf(sA[i], C, nm)); sB[i] = __builtin_amdgcn_exp2f(fmaf(sB[i], C, nm)); l += sA[i] + sB[i]; }
;     ...
;       bf16x8 pf[4];
;       { u32x4 w;
;         w.x = cvtpk(sA[0], sA[1]); w.y = cvtpk(sA[2], sA[3]); w.z = cvtpk(sA[4], sA[5]); w.w = cvtpk(sA[6], sA[7]); pf[0] = __builtin_bit_cast(bf16x8, w);
;         w.x = cvtpk(sA[8], sA[9]); w.y = cvtpk(sA[10], sA[11]); w.z = cvtpk(sA[12], sA[13]); w.w = cvtpk(sA[14], sA[15]); pf[1] = __builtin_bit_cast(bf16x8, w);
;         w.x = cvtpk(sB[0], sB[1]); w.y = cvtpk(sB[2], sB[3]); w.z = cvtpk(sB[4], sB[5]); w.w = cvtpk(sB[6], sB[7]); pf[2] = __builtin_bit_cast(bf16x8, w);
.Lds1_sk0:
	v_exp_f32_e32 v50, v50
	v_exp_f32_e32 v51, v51
	v_exp_f32_e32 v52, v52
	v_exp_f32_e32 v53, v53
	v_exp_f32_e32 v54, v54
	v_exp_f32_e32 v55, v55
	v_exp_f32_e32 v56, v56
	v_exp_f32_e32 v57, v57
	s_waitcnt lgkmcnt(13)
	v_mfma_f32_32x32x16_bf16 v[136:151], v[106:109], v[66:69], 0
	v_cvt_pk_bf16_f32 v152, v50, v51
	v_cvt_pk_bf16_f32 v153, v52, v53
	v_cvt_pk_bf16_f32 v154, v54, v55
	v_cvt_pk_bf16_f32 v155, v56, v57
	v_add_f32_e32 v115, v50, v115
	v_add_f32_e32 v115, v51, v115
	s_waitcnt lgkmcnt(12)
	v_mfma_f32_32x32x16_bf16 v[136:151], v[110:113], v[70:73], v[136:151]
	v_exp_f32_e32 v58, v58
	v_exp_f32_e32 v59, v59
	v_exp_f32_e32 v60, v60
	v_exp_f32_e32 v61, v61
	v_add_f32_e32 v164, v52, v164
	v_add_f32_e32 v164, v53, v164
	s_waitcnt lgkmcnt(11)
	v_mfma_f32_32x32x16_bf16 v[136:151], v[120:123], v[74:77], v[136:151]
	v_exp_f32_e32 v62, v62
	v_exp_f32_e32 v63, v63
	v_exp_f32_e32 v64, v64
	v_exp_f32_e32 v65, v65
	v_add_f32_e32 v115, v54, v115
	v_add_f32_e32 v115, v55, v115
	s_waitcnt lgkmcnt(10)
	v_mfma_f32_32x32x16_bf16 v[136:151], v[124:127], v[78:81], v[136:151]
	ds_read_b128 v[106:109], v0 offset:20480
	ds_read_b128 v[110:113], v102 offset:20480
	ds_read_b128 v[120:123], v103 offset:20480
	ds_read_b128 v[124:127], v104 offset:20480
	v_add_f32_e32 v164, v56, v164
	v_add_f32_e32 v164, v57, v164
	s_waitcnt lgkmcnt(12)
	v_mfma_f32_32x32x16_bf16 v[18:33], v[168:171], v[152:155], v[18:33]
	v_cvt_pk_bf16_f32 v156, v58, v59
	v_cvt_pk_bf16_f32 v157, v60, v61
	v_cvt_pk_bf16_f32 v158, v62, v63
	v_cvt_pk_bf16_f32 v159, v64, v65
	v_add_f32_e32 v115, v58, v115
	v_add_f32_e32 v115, v59, v115
	s_waitcnt lgkmcnt(10)
	v_mfma_f32_32x32x16_bf16 v[2:17], v[172:175], v[152:155], v[2:17]
	v_add_f32_e32 v164, v60, v164
	v_add_f32_e32 v164, v61, v164
	v_add_f32_e32 v164, v62, v164
	v_add_f32_e32 v164, v63, v164
	v_add_f32_e32 v164, v64, v164
	v_add_f32_e32 v164, v65, v164
	s_waitcnt lgkmcnt(8)
	v_mfma_f32_32x32x16_bf16 v[18:33], v[176:179], v[156:159], v[18:33]
	v_exp_f32_e32 v34, v34
	v_exp_f32_e32 v35, v35
	v_exp_f32_e32 v36, v36
	v_exp_f32_e32 v37, v37
	s_waitcnt lgkmcnt(6)
	v_mfma_f32_32x32x16_bf16 v[2:17], v[180:183], v[156:159], v[2:17]
	ds_read_b64_tr_b16 v[168:169], v98 offset:12288
	ds_read_b64_tr_b16 v[170:171], v98 offset:12544
	ds_read_b64_tr_b16 v[172:173], v98 offset:12800
	ds_read_b64_tr_b16 v[174:175], v98 offset:13056
	ds_read_b64_tr_b16 v[176:177], v98 offset:14336
	ds_read_b64_tr_b16 v[178:179], v98 offset:14592
	ds_read_b64_tr_b16 v[180:181], v98 offset:14848
	ds_read_b64_tr_b16 v[182:183], v98 offset:15104
	v_exp_f32_e32 v38, v38
	v_exp_f32_e32 v39, v39
	v_exp_f32_e32 v40, v40
	v_exp_f32_e32 v41, v41
	s_waitcnt lgkmcnt(11)
	v_mfma_f32_32x32x16_bf16 v[50:65], v[106:109], v[66:69], 0
	v_cvt_pk_bf16_f32 v160, v34, v35
	v_cvt_pk_bf16_f32 v161, v36, v37
	v_cvt_pk_bf16_f32 v162, v38, v39
	v_cvt_pk_bf16_f32 v163, v40, v41
	v_add_f32_e32 v115, v34, v115
	v_add_f32_e32 v115, v35, v115
	s_waitcnt lgkmcnt(10)
	v_mfma_f32_32x32x16_bf16 v[50:65], v[110:113], v[70:73], v[50:65]
	v_exp_f32_e32 v42, v42
	v_exp_f32_e32 v43, v43
	v_exp_f32_e32 v44, v44
	v_exp_f32_e32 v45, v45
	v_add_f32_e32 v164, v36, v164
	v_add_f32_e32 v164, v37, v164
	s_waitcnt lgkmcnt(9)
	v_mfma_f32_32x32x16_bf16 v[50:65], v[120:123], v[74:77], v[50:65]
	v_exp_f32_e32 v46, v46
	v_exp_f32_e32 v47, v47
	v_exp_f32_e32 v48, v48
	v_exp_f32_e32 v49, v49
	v_add_f32_e32 v115, v38, v115
	v_add_f32_e32 v115, v39, v115
	s_waitcnt lgkmcnt(8)
	v_mfma_f32_32x32x16_bf16 v[50:65], v[124:127], v[78:81], v[50:65]
	v_cvt_pk_bf16_f32 v184, v42, v43
	v_cvt_pk_bf16_f32 v185, v44, v45
	v_cvt_pk_bf16_f32 v186, v46, v47
	v_cvt_pk_bf16_f32 v187, v48, v49
	v_add_f32_e32 v164, v40, v164
	v_add_f32_e32 v164, v41, v164
	s_waitcnt lgkmcnt(6)
	v_mfma_f32_32x32x16_bf16 v[18:33], v[168:171], v[160:163], v[18:33]
	v_add_f32_e32 v115, v42, v115
	v_add_f32_e32 v115, v43, v115
	v_add_f32_e32 v115, v44, v115
	v_add_f32_e32 v115, v45, v115
	s_waitcnt lgkmcnt(4)
	v_mfma_f32_32x32x16_bf16 v[2:17], v[172:175], v[160:163], v[2:17]
	v_add_f32_e32 v164, v46, v164
	v_add_f32_e32 v164, v47, v164
	v_add_f32_e32 v164, v48, v164
	v_add_f32_e32 v164, v49, v164
	s_waitcnt lgkmcnt(2)
	v_mfma_f32_32x32x16_bf16 v[18:33], v[176:179], v[184:187], v[18:33]
	s_waitcnt lgkmcnt(0)
	v_mfma_f32_32x32x16_bf16 v[2:17], v[180:183], v[184:187], v[2:17]
	s_waitcnt lgkmcnt(0)
	s_barrier
	s_add_i32 s30, s30, 1
	s_cmp_ge_u32 s30, s96
	s_cbranch_scc1 .Lds1_done
	ds_read_b128 v[106:109], v0 offset:32768
	ds_read_b128 v[110:113], v102 offset:32768
	ds_read_b128 v[120:123], v103 offset:32768
	ds_read_b128 v[124:127], v104 offset:32768
	ds_read_b64_tr_b16 v[168:169], v98 offset:24576
	ds_read_b64_tr_b16 v[170:171], v98 offset:24832
	ds_read_b64_tr_b16 v[172:173], v98 offset:25088
	ds_read_b64_tr_b16 v[174:175], v98 offset:25344
	ds_read_b64_tr_b16 v[176:177], v98 offset:26624
	ds_read_b64_tr_b16 v[178:179], v98 offset:26880
	ds_read_b64_tr_b16 v[180:181], v98 offset:27136
	ds_read_b64_tr_b16 v[182:183], v98 offset:27392
	s_waitcnt vmcnt(0)
	ds_write_b128 v100, v[82:85] offset:0
	ds_write_b128 v165, v[86:89] offset:8192
	s_add_i32 s31, s30, 3
	s_cmp_lt_u32 s31, s96
	s_cbranch_scc0 .Lds1_sk1
	global_load_dwordx4 v[82:85], v[92:93], off offset:1024
	global_load_dwordx4 v[86:89], v[90:91], off offset:1280
	v_lshl_add_u64 v[92:93], v[92:93], 0, s[10:11]
	v_lshl_add_u64 v[90:91], v[90:91], 0, s[10:11]
; template <int DV, int NK, int MODE, bool FIXM, int GRP>
; DI void attn_job(char* lds_wg, const AttnJob& J) {
;     ...
;       if (NDV == 2 || FIXM) {
;         bf16x8 ka[4], kb[4];
; #pragma unroll
;         for (int ds = 0; ds < 4; ++ds) { const int co = ((2 * ds + h) ^ ((r >> 1) & 7)) << 4; ka[ds] = *(const bf16x8*)(Kl + co); kb[ds] = *(const bf16x8*)(Kl + 4096 + co); }
; #pragma unroll
;         for (int ds = 0; ds < 4; ++ds) { sA = MFMA32(ka[ds], qf[ds], sA); sB = MFMA32(kb[ds], qf[ds], sB); }
;         __builtin_amdgcn_sched_group_barrier(0x100, 4, 0); __builtin_amdgcn_sched_group_barrier(0x008, 2, 0);
;         __builtin_amdgcn_sched_group_barrier(0x100, 2, 0); __builtin_amdgcn_sched_group_barrier(0x008, 2, 0);
;         __builtin_amdgcn_sched_group_barrier(0x100, 2, 0); __builtin_amdgcn_sched_group_barrier(0x008, 4, 0);
;       } else {
; #pragma unroll
;         for (int ds = 0; ds < 4; ++ds) {
;           const int co = ((2 * ds + h) ^ ((r >> 1) & 7)) << 4;
;           const bf16x8 ka = *(const bf16x8*)(Kl + co), kb = *(const bf16x8*)(Kl + 4096 + co);
;           sA = MFMA32(ka, qf[ds], sA); sB = MFMA32(kb, qf[ds], sB);
;         }
;       }
;       if (MODE == AM_SWA) {
;         const int qa = J.qpos0 + r, kbase = tile * 64 + 8 * h;
; #pragma unroll
;         for (int i = 0; i < 16; ++i) {
;           const int ka_ = kbase + 16 * (i >> 3) + (i & 7);
;           int d0 = qa - ka_; d0 = d0 < 0 ? -d0 : d0; if (d0 > 128) sA[i] = -INFINITY;
;           int d1 = qa - (ka_ + 32); d1 = d1 < 0 ? -d1 : d1; if (d1 > 128) sB[i] = -INFINITY;
;         }
;       }
;       if (FIXM) {
;         const float nm = -J.m_init;
; #pragma unroll
;         for (int i = 0; i < 16; ++i) { sA[i] = __builtin_amdgcn_exp2f(fmaf(sA[i], C, nm)); sB[i] = __builtin_amdgcn_exp2f(fmaf(sB[i], C, nm)); l += sA[i] + sB[i]; }
;     ...
;       bf16x8 pf[4];
;       { u32x4 w;
;         w.x = cvtpk(sA[0], sA[1]); w.y = cvtpk(sA[2], sA[3]); w.z = cvtpk(sA[4], sA[5]); w.w = cvtpk(sA[6], sA[7]); pf[0] = __builtin_bit_cast(bf16x8, w);
;         w.x = cvtpk(sA[8], sA[9]); w.y = cvtpk(sA[10], sA[11]); w.z = cvtpk(sA[12], sA[13]); w.w = cvtpk(sA[14], sA[15]); pf[1] = __builtin_bit_cast(bf16x8, w);
;         w.x = cvtpk(sB[0], sB[1]); w.y = cvtpk(sB[2], sB[3]); w.z = cvtpk(sB[4], sB[5]); w.w = cvtpk(sB[6], sB[7]); pf[2] = __builtin_bit_cast(bf16x8, w);
.Lds1_sk1:
	v_exp_f32_e32 v136, v136
	v_exp_f32_e32 v137, v137
	v_exp_f32_e32 v138, v138
	v_exp_f32_e32 v139, v139
	v_exp_f32_e32 v140, v140
	v_exp_f32_e32 v141, v141
	v_exp_f32_e32 v142, v142
	v_exp_f32_e32 v143, v143
	s_waitcnt lgkmcnt(13)
	v_mfma_f32_32x32x16_bf16 v[34:49], v[106:109], v[66:69], 0
	v_cvt_pk_bf16_f32 v152, v136, v137
	v_cvt_pk_bf16_f32 v153, v138, v139
	v_cvt_pk_bf16_f32 v154, v140, v141
	v_cvt_pk_bf16_f32 v155, v142, v143
	v_add_f32_e32 v115, v136, v115
	v_add_f32_e32 v115, v137, v115
	s_waitcnt lgkmcnt(12)
	v_mfma_f32_32x32x16_bf16 v[34:49], v[110:113], v[70:73], v[34:49]
	v_exp_f32_e32 v144, v144
	v_exp_f32_e32 v145, v145
	v_exp_f32_e32 v146, v146
	v_exp_f32_e32 v147, v147
	v_add_f32_e32 v164, v138, v164
	v_add_f32_e32 v164, v139, v164
	s_waitcnt lgkmcnt(11)
	v_mfma_f32_32x32x16_bf16 v[34:49], v[120:123], v[74:77], v[34:49]
	v_exp_f32_e32 v148, v148
	v_exp_f32_e32 v149, v149
	v_exp_f32_e32 v150, v150
	v_exp_f32_e32 v151, v151
	v_add_f32_e32 v115, v140, v115
	v_add_f32_e32 v115, v141, v115
	s_waitcnt lgkmcnt(10)
	v_mfma_f32_32x32x16_bf16 v[34:49], v[124:127], v[78:81], v[34:49]
	ds_read_b128 v[106:109], v0 offset:36864
	ds_read_b128 v[110:113], v102 offset:36864
	ds_read_b128 v[120:123], v103 offset:36864
	ds_read_b128 v[124:127], v104 offset:36864
	v_add_f32_e32 v164, v142, v164
	v_add_f32_e32 v164, v143, v164
	s_waitcnt lgkmcnt(12)
	v_mfma_f32_32x32x16_bf16 v[18:33], v[168:171], v[152:155], v[18:33]
	v_cvt_pk_bf16_f32 v156, v144, v145
	v_cvt_pk_bf16_f32 v157, v146, v147
	v_cvt_pk_bf16_f32 v158, v148, v149
	v_cvt_pk_bf16_f32 v159, v150, v151
	v_add_f32_e32 v115, v144, v115
	v_add_f32_e32 v115, v145, v115
	s_waitcnt lgkmcnt(10)
	v_mfma_f32_32x32x16_bf16 v[2:17], v[172:175], v[152:155], v[2:17]
	v_add_f32_e32 v164, v146, v164
	v_add_f32_e32 v164, v147, v164
	v_add_f32_e32 v164, v148, v164
	v_add_f32_e32 v164, v149, v164
	v_add_f32_e32 v164, v150, v164
	v_add_f32_e32 v164, v151, v164
	s_waitcnt lgkmcnt(8)
	v_mfma_f32_32x32x16_bf16 v[18:33], v[176:179], v[156:159], v[18:33]
	v_exp_f32_e32 v50, v50
	v_exp_f32_e32 v51, v51
	v_exp_f32_e32 v52, v52
	v_exp_f32_e32 v53, v53
	s_waitcnt lgkmcnt(6)
	v_mfma_f32_32x32x16_bf16 v[2:17], v[180:183], v[156:159], v[2:17]
	ds_read_b64_tr_b16 v[168:169], v98 offset:28672
	ds_read_b64_tr_b16 v[170:171], v98 offset:28928
	ds_read_b64_tr_b16 v[172:173], v98 offset:29184
	ds_read_b64_tr_b16 v[174:175], v98 offset:29440
	ds_read_b64_tr_b16 v[176:177], v98 offset:30720
	ds_read_b64_tr_b16 v[178:179], v98 offset:30976
	ds_read_b64_tr_b16 v[180:181], v98 offset:31232
	ds_read_b64_tr_b16 v[182:183], v98 offset:31488
	v_exp_f32_e32 v54, v54
	v_exp_f32_e32 v55, v55
	v_exp_f32_e32 v56, v56
	v_exp_f32_e32 v57, v57
	s_waitcnt lgkmcnt(11)
	v_mfma_f32_32x32x16_bf16 v[136:151], v[106:109], v[66:69], 0
	v_cvt_pk_bf16_f32 v160, v50, v51
	v_cvt_pk_bf16_f32 v161, v52, v53
	v_cvt_pk_bf16_f32 v162, v54, v55
	v_cvt_pk_bf16_f32 v163, v56, v57
	v_add_f32_e32 v115, v50, v115
	v_add_f32_e32 v115, v51, v115
	s_waitcnt lgkmcnt(10)
	v_mfma_f32_32x32x16_bf16 v[136:151], v[110:113], v[70:73], v[136:151]
	v_exp_f32_e32 v58, v58
	v_exp_f32_e32 v59, v59
	v_exp_f32_e32 v60, v60
	v_exp_f32_e32 v61, v61
	v_add_f32_e32 v164, v52, v164
	v_add_f32_e32 v164, v53, v164
	s_waitcnt lgkmcnt(9)
	v_mfma_f32_32x32x16_bf16 v[136:151], v[120:123], v[74:77], v[136:151]
	v_exp_f32_e32 v62, v62
	v_exp_f32_e32 v63, v63
	v_exp_f32_e32 v64, v64
	v_exp_f32_e32 v65, v65
	v_add_f32_e32 v115, v54, v115
	v_add_f32_e32 v115, v55, v115
	s_waitcnt lgkmcnt(8)
	v_mfma_f32_32x32x16_bf16 v[136:151], v[124:127], v[78:81], v[136:151]
	v_cvt_pk_bf16_f32 v184, v58, v59
	v_cvt_pk_bf16_f32 v185, v60, v61
	v_cvt_pk_bf16_f32 v186, v62, v63
	v_cvt_pk_bf16_f32 v187, v64, v65
	v_add_f32_e32 v164, v56, v164
	v_add_f32_e32 v164, v57, v164
	s_waitcnt lgkmcnt(6)
	v_mfma_f32_32x32x16_bf16 v[18:33], v[168:171], v[160:163], v[18:33]
	v_add_f32_e32 v115, v58, v115
	v_add_f32_e32 v115, v59, v115
	v_add_f32_e32 v115, v60, v115
	v_add_f32_e32 v115, v61, v115
	s_waitcnt lgkmcnt(4)
	v_mfma_f32_32x32x16_bf16 v[2:17], v[172:175], v[160:163], v[2:17]
	v_add_f32_e32 v164, v62, v164
	v_add_f32_e32 v164, v63, v164
	v_add_f32_e32 v164, v64, v164
	v_add_f32_e32 v164, v65, v164
	s_waitcnt lgkmcnt(2)
	v_mfma_f32_32x32x16_bf16 v[18:33], v[176:179], v[184:187], v[18:33]
	s_waitcnt lgkmcnt(0)
	v_mfma_f32_32x32x16_bf16 v[2:17], v[180:183], v[184:187], v[2:17]
	s_waitcnt lgkmcnt(0)
	s_barrier
	s_add_i32 s30, s30, 1
	s_cmp_ge_u32 s30, s96
	s_cbranch_scc1 .Lds1_done
	ds_read_b128 v[106:109], v0 offset:0
	ds_read_b128 v[110:113], v102 offset:0
	ds_read_b128 v[120:123], v103 offset:0
	ds_read_b128 v[124:127], v104 offset:0
	ds_read_b64_tr_b16 v[168:169], v98 offset:40960
	ds_read_b64_tr_b16 v[170:171], v98 offset:41216
	ds_read_b64_tr_b16 v[172:173], v98 offset:41472
	ds_read_b64_tr_b16 v[174:175], v98 offset:41728
	ds_read_b64_tr_b16 v[176:177], v98 offset:43008
	ds_read_b64_tr_b16 v[178:179], v98 offset:43264
	ds_read_b64_tr_b16 v[180:181], v98 offset:43520
	ds_read_b64_tr_b16 v[182:183], v98 offset:43776
	s_waitcnt vmcnt(0)
	ds_write_b128 v100, v[82:85] offset:16384
	ds_write_b128 v165, v[86:89] offset:24576
	s_add_i32 s31, s30, 3
	s_cmp_lt_u32 s31, s96
	s_cbranch_scc0 .Lds1_sk2
	global_load_dwordx4 v[82:85], v[92:93], off offset:1024
	global_load_dwordx4 v[86:89], v[90:91], off offset:1280
	v_lshl_add_u64 v[92:93], v[92:93], 0, s[10:11]
	v_lshl_add_u64 v[90:91], v[90:91], 0, s[10:11]
; template <int DV, int NK, int MODE, bool FIXM, int GRP>
; DI void attn_job(char* lds_wg, const AttnJob& J) {
;     ...
;       if (NDV == 2 || FIXM) {
;         bf16x8 ka[4], kb[4];
; #pragma unroll
;         for (int ds = 0; ds < 4; ++ds) { const int co = ((2 * ds + h) ^ ((r >> 1) & 7)) << 4; ka[ds] = *(const bf16x8*)(Kl + co); kb[ds] = *(const bf16x8*)(Kl + 4096 + co); }
; #pragma unroll
;         for (int ds = 0; ds < 4; ++ds) { sA = MFMA32(ka[ds], qf[ds], sA); sB = MFMA32(kb[ds], qf[ds], sB); }
;         __builtin_amdgcn_sched_group_barrier(0x100, 4, 0); __builtin_amdgcn_sched_group_barrier(0x008, 2, 0);
;         __builtin_amdgcn_sched_group_barrier(0x100, 2, 0); __builtin_amdgcn_sched_group_barrier(0x008, 2, 0);
;         __builtin_amdgcn_sched_group_barrier(0x100, 2, 0); __builtin_amdgcn_sched_group_barrier(0x008, 4, 0);
;       } else {
; #pragma unroll
;         for (int ds = 0; ds < 4; ++ds) {
;           const int co = ((2 * ds + h) ^ ((r >> 1) & 7)) << 4;
;           const bf16x8 ka = *(const bf16x8*)(Kl + co), kb = *(const bf16x8*)(Kl + 4096 + co);
;           sA = MFMA32(ka, qf[ds], sA); sB = MFMA32(kb, qf[ds], sB);
;         }
;       }
;       if (MODE == AM_SWA) {
;         const int qa = J.qpos0 + r, kbase = tile * 64 + 8 * h;
; #pragma unroll
;         for (int i = 0; i < 16; ++i) {
;           const int ka_ = kbase + 16 * (i >> 3) + (i & 7);
;           int d0 = qa - ka_; d0 = d0 < 0 ? -d0 : d0; if (d0 > 128) sA[i] = -INFINITY;
;           int d1 = qa - (ka_ + 32); d1 = d1 < 0 ? -d1 : d1; if (d1 > 128) sB[i] = -INFINITY;
;         }
;       }
;       if (FIXM) {
;         const float nm = -J.m_init;
; #pragma unroll
;         for (int i = 0; i < 16; ++i) { sA[i] = __builtin_amdgcn_exp2f(fmaf(sA[i], C, nm)); sB[i] = __builtin_amdgcn_exp2f(fmaf(sB[i], C, nm)); l += sA[i] + sB[i]; }
;     ...
;       bf16x8 pf[4];
;       { u32x4 w;
;         w.x = cvtpk(sA[0], sA[1]); w.y = cvtpk(sA[2], sA[3]); w.z = cvtpk(sA[4], sA[5]); w.w = cvtpk(sA[6], sA[7]); pf[0] = __builtin_bit_cast(bf16x8, w);
;         w.x = cvtpk(sA[8], sA[9]); w.y = cvtpk(sA[10], sA[11]); w.z = cvtpk(sA[12], sA[13]); w.w = cvtpk(sA[14], sA[15]); pf[1] = __builtin_bit_cast(bf16x8, w);
;         w.x = cvtpk(sB[0], sB[1]); w.y = cvtpk(sB[2], sB[3]); w.z = cvtpk(sB[4], sB[5]); w.w = cvtpk(sB[6], sB[7]); pf[2] = __builtin_bit_cast(bf16x8, w);
.Lds1_sk2:
	v_exp_f32_e32 v34, v34
	v_exp_f32_e32 v35, v35
	v_exp_f32_e32 v36, v36
	v_exp_f32_e32 v37, v37
	v_exp_f32_e32 v38, v38
	v_exp_f32_e32 v39, v39
	v_exp_f32_e32 v40, v40
	v_exp_f32_e32 v41, v41
	s_waitcnt lgkmcnt(13)
	v_mfma_f32_32x32x16_bf16 v[50:65], v[106:109], v[66:69], 0
	v_cvt_pk_bf16_f32 v152, v34, v35
	v_cvt_pk_bf16_f32 v153, v36, v37
	v_cvt_pk_bf16_f32 v154, v38, v39
	v_cvt_pk_bf16_f32 v155, v40, v41
	v_add_f32_e32 v115, v34, v115
	v_add_f32_e32 v115, v35, v115
	s_waitcnt lgkmcnt(12)
	v_mfma_f32_32x32x16_bf16 v[50:65], v[110:113], v[70:73], v[50:65]
	v_exp_f32_e32 v42, v42
	v_exp_f32_e32 v43, v43
	v_exp_f32_e32 v44, v44
	v_exp_f32_e32 v45, v45
	v_add_f32_e32 v164, v36, v164
	v_add_f32_e32 v164, v37, v164
	s_waitcnt lgkmcnt(11)
	v_mfma_f32_32x32x16_bf16 v[50:65], v[120:123], v[74:77], v[50:65]
	v_exp_f32_e32 v46, v46
	v_exp_f32_e32 v47, v47
	v_exp_f32_e32 v48, v48
	v_exp_f32_e32 v49, v49
	v_add_f32_e32 v115, v38, v115
	v_add_f32_e32 v115, v39, v115
	s_waitcnt lgkmcnt(10)
	v_mfma_f32_32x32x16_bf16 v[50:65], v[124:127], v[78:81], v[50:65]
	ds_read_b128 v[106:109], v0 offset:4096
	ds_read_b128 v[110:113], v102 offset:4096
	ds_read_b128 v[120:123], v103 offset:4096
	ds_read_b128 v[124:127], v104 offset:4096
	v_add_f32_e32 v164, v40, v164
	v_add_f32_e32 v164, v41, v164
	s_waitcnt lgkmcnt(12)
	v_mfma_f32_32x32x16_bf16 v[18:33], v[168:171], v[152:155], v[18:33]
	v_cvt_pk_bf16_f32 v156, v42, v43
	v_cvt_pk_bf16_f32 v157, v44, v45
	v_cvt_pk_bf16_f32 v158, v46, v47
	v_cvt_pk_bf16_f32 v159, v48, v49
	v_add_f32_e32 v115, v42, v115
	v_add_f32_e32 v115, v43, v115
	s_waitcnt lgkmcnt(10)
	v_mfma_f32_32x32x16_bf16 v[2:17], v[172:175], v[152:155], v[2:17]
	v_add_f32_e32 v164, v44, v164
	v_add_f32_e32 v164, v45, v164
	v_add_f32_e32 v164, v46, v164
	v_add_f32_e32 v164, v47, v164
	v_add_f32_e32 v164, v48, v164
	v_add_f32_e32 v164, v49, v164
	s_waitcnt lgkmcnt(8)
	v_mfma_f32_32x32x16_bf16 v[18:33], v[176:179], v[156:159], v[18:33]
	v_exp_f32_e32 v136, v136
	v_exp_f32_e32 v137, v137
	v_exp_f32_e32 v138, v138
	v_exp_f32_e32 v139, v139
	s_waitcnt lgkmcnt(6)
	v_mfma_f32_32x32x16_bf16 v[2:17], v[180:183], v[156:159], v[2:17]
	ds_read_b64_tr_b16 v[168:169], v98 offset:45056
	ds_read_b64_tr_b16 v[170:171], v98 offset:45312
	ds_read_b64_tr_b16 v[172:173], v98 offset:45568
	ds_read_b64_tr_b16 v[174:175], v98 offset:45824
	ds_read_b64_tr_b16 v[176:177], v98 offset:47104
	ds_read_b64_tr_b16 v[178:179], v98 offset:47360
	ds_read_b64_tr_b16 v[180:181], v98 offset:47616
	ds_read_b64_tr_b16 v[182:183], v98 offset:47872
	v_exp_f32_e32 v140, v140
	v_exp_f32_e32 v141, v141
	v_exp_f32_e32 v142, v142
	v_exp_f32_e32 v143, v143
	s_waitcnt lgkmcnt(11)
	v_mfma_f32_32x32x16_bf16 v[34:49], v[106:109], v[66:69], 0
	v_cvt_pk_bf16_f32 v160, v136, v137
	v_cvt_pk_bf16_f32 v161, v138, v139
	v_cvt_pk_bf16_f32 v162, v140, v141
	v_cvt_pk_bf16_f32 v163, v142, v143
	v_add_f32_e32 v115, v136, v115
	v_add_f32_e32 v115, v137, v115
	s_waitcnt lgkmcnt(10)
	v_mfma_f32_32x32x16_bf16 v[34:49], v[110:113], v[70:73], v[34:49]
	v_exp_f32_e32 v144, v144
	v_exp_f32_e32 v145, v145
	v_exp_f32_e32 v146, v146
	v_exp_f32_e32 v147, v147
	v_add_f32_e32 v164, v138, v164
	v_add_f32_e32 v164, v139, v164
	s_waitcnt lgkmcnt(9)
	v_mfma_f32_32x32x16_bf16 v[34:49], v[120:123], v[74:77], v[34:49]
	v_exp_f32_e32 v148, v148
	v_exp_f32_e32 v149, v149
	v_exp_f32_e32 v150, v150
	v_exp_f32_e32 v151, v151
	v_add_f32_e32 v115, v140, v115
	v_add_f32_e32 v115, v141, v115
	s_waitcnt lgkmcnt(8)
	v_mfma_f32_32x32x16_bf16 v[34:49], v[124:127], v[78:81], v[34:49]
	v_cvt_pk_bf16_f32 v184, v144, v145
	v_cvt_pk_bf16_f32 v185, v146, v147
	v_cvt_pk_bf16_f32 v186, v148, v149
	v_cvt_pk_bf16_f32 v187, v150, v151
	v_add_f32_e32 v164, v142, v164
	v_add_f32_e32 v164, v143, v164
	s_waitcnt lgkmcnt(6)
	v_mfma_f32_32x32x16_bf16 v[18:33], v[168:171], v[160:163], v[18:33]
	v_add_f32_e32 v115, v144, v115
	v_add_f32_e32 v115, v145, v115
	v_add_f32_e32 v115, v146, v115
	v_add_f32_e32 v115, v147, v115
	s_waitcnt lgkmcnt(4)
	v_mfma_f32_32x32x16_bf16 v[2:17], v[172:175], v[160:163], v[2:17]
	v_add_f32_e32 v164, v148, v164
	v_add_f32_e32 v164, v149, v164
	v_add_f32_e32 v164, v150, v164
	v_add_f32_e32 v164, v151, v164
	s_waitcnt lgkmcnt(2)
	v_mfma_f32_32x32x16_bf16 v[18:33], v[176:179], v[184:187], v[18:33]
	s_waitcnt lgkmcnt(0)
	v_mfma_f32_32x32x16_bf16 v[2:17], v[180:183], v[184:187], v[2:17]
	s_waitcnt lgkmcnt(0)
	s_barrier
	s_add_i32 s30, s30, 1
	s_cmp_ge_u32 s30, s96
	s_cbranch_scc1 .Lds1_done
	s_branch .Lds1_loop
